# removed the cooperative-groups grid sync at kernel entry (XCD barrier census completes lazily)
# baseline (speedup 1.0000x reference)
; __global__ void __launch_bounds__(NWAVES * 64, 2) hybrid_fwd(Args A) {
;     ...
;     const bool multi = (A.ph_hi - A.ph_lo) > 1;
;     if (threadIdx.x < 16) MISC[threadIdx.x] = 0u;
;     __syncthreads();
;     XcdBarrier bar; bar.bar = (unsigned*)(A.ws + WS_CTL) + 4096; bar.x = 0; bar.st = MISC + 8;
;     if (multi) { bar = xcd_barrier_post((unsigned*)(A.ws + WS_CTL) + 4096, MISC + 8);
;                  cg::this_grid().sync(); }
.LBB0_6:
	s_or_b64 exec, exec, s[2:3]
.LBB0_17:
	s_load_dwordx16 s[0:15], s[62:63], 0x0
	s_cmp_lt_i32 s56, 1
	s_waitcnt lgkmcnt(0)
	v_writelane_b32 v254, s0, 9
	s_nop 1
	v_writelane_b32 v254, s1, 10
	v_writelane_b32 v254, s2, 11
	v_writelane_b32 v254, s3, 12
	v_writelane_b32 v254, s4, 13
	v_writelane_b32 v254, s5, 14
	v_writelane_b32 v254, s6, 15
	v_writelane_b32 v254, s7, 16
	v_writelane_b32 v254, s8, 17
	v_writelane_b32 v254, s9, 18
	v_writelane_b32 v254, s10, 19
	v_writelane_b32 v254, s11, 20
	v_writelane_b32 v254, s12, 21
	v_writelane_b32 v254, s13, 22
	v_writelane_b32 v254, s14, 23
	v_writelane_b32 v254, s15, 24
	s_cselect_b64 s[0:1], -1, 0
	s_cmp_gt_i32 s57, 0
	s_cselect_b64 s[2:3], -1, 0
	s_and_b64 s[4:5], s[0:1], s[2:3]
	s_andn2_b64 vcc, exec, s[4:5]
	s_cbranch_vccnz .LBB0_87
	v_readlane_b32 s0, v254, 8
	s_andn2_b32 s0, s0, 63
	v_mbcnt_lo_u32_b32 v0, -1, 0
	v_mbcnt_hi_u32_b32 v0, -1, v0
	s_nop 0
	v_add_u32_e32 v65, s0, v0
	s_load_dword s70, s[62:63], 0xb8
	v_readfirstlane_b32 s0, v65
	s_waitcnt lgkmcnt(0)
	s_and_b32 s1, s70, 7
	s_cmp_lg_u32 s1, 0
	s_mov_b32 s1, s97
	s_cbranch_scc1 .LBB0_20
	s_ashr_i32 s2, s97, 31
	s_lshr_b32 s2, s2, 29
	s_add_i32 s2, s97, s2
	s_ashr_i32 s3, s2, 3
	s_and_b32 s2, s2, -8
	s_ashr_i32 s1, s70, 3
	s_sub_i32 s2, s97, s2
	s_mul_i32 s1, s1, s2
	s_add_i32 s1, s1, s3
